# seam: L1 invalidate moved to idle wave 1 right after first WG barrier (off thread-0 critical path)
# speedup vs baseline: 1.0009x; 1.0009x over previous
; __device__ __forceinline__ unsigned xb_ld(unsigned* p)              { return __hip_atomic_load(p, __ATOMIC_RELAXED, __HIP_MEMORY_SCOPE_AGENT); }
; #define XB_SPIN(cond, bar) do { unsigned _sp = 0; while (cond) { __builtin_amdgcn_s_sleep(1); \
;     if ((++_sp & 255u) == 0u) { if (xb_ld(&(bar)[XB_TMO])) break; if (_sp > XB_SPIN_CAP) { atomicAdd(&(bar)[XB_TMO], 1u); break; } } } } while (0)
; __device__ __forceinline__ void xcd_barrier(const XcdBarrier& b) {
;     ...
;             XB_SPIN(xb_ld(&bar[XB_XGEN(b.x)]) == gen, bar);
;             __builtin_amdgcn_fence(__ATOMIC_ACQUIRE, "agent");
;             asm volatile("s_waitcnt vmcnt(0)" ::: "memory");
.LBB0_320:
	s_or_b64 exec, exec, s[14:15]
	s_waitcnt vmcnt(0)
	s_waitcnt vmcnt(0)

; __device__ __forceinline__ unsigned xb_ld(unsigned* p)              { return __hip_atomic_load(p, __ATOMIC_RELAXED, __HIP_MEMORY_SCOPE_AGENT); }
; __device__ __forceinline__ unsigned xb_add(unsigned* p, unsigned v) { return __hip_atomic_fetch_add(p, v, __ATOMIC_RELAXED, __HIP_MEMORY_SCOPE_AGENT); }
; #define XB_SPIN(cond, bar) do { unsigned _sp = 0; while (cond) { __builtin_amdgcn_s_sleep(1); \
;     if ((++_sp & 255u) == 0u) { if (xb_ld(&(bar)[XB_TMO])) break; if (_sp > XB_SPIN_CAP) { atomicAdd(&(bar)[XB_TMO], 1u); break; } } } } while (0)
; __device__ __forceinline__ void xcd_barrier(const XcdBarrier& b) {
;     ...
;             const unsigned og = xb_add(&bar[XB_TOP], 1u);
;             const unsigned tg = og / nx;
;             if (og + 1u == (tg + 1u) * nx) xb_add(&bar[XB_TOPGEN], 1u);
;             else XB_SPIN(xb_ld(&bar[XB_TOPGEN]) == tg, bar);
;             __builtin_amdgcn_fence(__ATOMIC_ACQUIRE, "agent");
;             xb_add(&bar[XB_XGEN(b.x)], 1u);
;             asm volatile("s_waitcnt vmcnt(0)" ::: "memory");
;         } else {
;             XB_SPIN(xb_ld(&bar[XB_XGEN(b.x)]) == gen, bar);
;             __builtin_amdgcn_fence(__ATOMIC_ACQUIRE, "agent");
;             asm volatile("s_waitcnt vmcnt(0)" ::: "memory");
;         }
;     }
;     __syncthreads();
.LBB0_338:
	s_or_b64 exec, exec, s[10:11]
	v_mov_b32_e32 v2, 0x2000
	v_mov_b32_e32 v3, 1
	s_waitcnt vmcnt(0)
	global_atomic_add v2, v3, s[4:5] offset:1024
	s_waitcnt vmcnt(0)
	s_branch .LBB0_339
.Lseam_inv_0:
	v_readfirstlane_b32 s98, v1
	s_nop 0
	s_lshr_b32 s98, s98, 6
	s_cmp_lg_u32 s98, 1
	s_cbranch_scc1 .LBB0_339
	s_mov_b64 exec, -1
	buffer_inv sc1
	s_waitcnt vmcnt(0)

; __device__ __forceinline__ unsigned xb_add(unsigned* p, unsigned v) { return __hip_atomic_fetch_add(p, v, __ATOMIC_RELAXED, __HIP_MEMORY_SCOPE_AGENT); }
; __device__ __forceinline__ void xcd_barrier(const XcdBarrier& b) {
;     ...
;             __builtin_amdgcn_fence(__ATOMIC_ACQUIRE, "agent");
;             xb_add(&bar[XB_XGEN(b.x)], 1u);
;             asm volatile("s_waitcnt vmcnt(0)" ::: "memory");
.LBB0_569:
	s_or_b64 exec, exec, s[12:13]
	v_mov_b32_e32 v2, 0x2000
	v_mov_b32_e32 v3, 1
	s_waitcnt vmcnt(0)
	global_atomic_add v2, v3, s[4:5] offset:1024
	s_waitcnt vmcnt(0)
	s_branch .LBB0_570

; __device__ __forceinline__ unsigned xb_ld(unsigned* p)              { return __hip_atomic_load(p, __ATOMIC_RELAXED, __HIP_MEMORY_SCOPE_AGENT); }
; #define XB_SPIN(cond, bar) do { unsigned _sp = 0; while (cond) { __builtin_amdgcn_s_sleep(1); \
;     if ((++_sp & 255u) == 0u) { if (xb_ld(&(bar)[XB_TMO])) break; if (_sp > XB_SPIN_CAP) { atomicAdd(&(bar)[XB_TMO], 1u); break; } } } } while (0)
; __device__ __forceinline__ void xcd_barrier(const XcdBarrier& b) {
;     ...
;             XB_SPIN(xb_ld(&bar[XB_XGEN(b.x)]) == gen, bar);
;             __builtin_amdgcn_fence(__ATOMIC_ACQUIRE, "agent");
;             asm volatile("s_waitcnt vmcnt(0)" ::: "memory");
.LBB0_987:
	s_or_b64 exec, exec, s[8:9]
	s_waitcnt vmcnt(0)
	s_waitcnt vmcnt(0)

; __device__ __forceinline__ unsigned xb_add(unsigned* p, unsigned v) { return __hip_atomic_fetch_add(p, v, __ATOMIC_RELAXED, __HIP_MEMORY_SCOPE_AGENT); }
; __device__ __forceinline__ void xcd_barrier(const XcdBarrier& b) {
;     ...
;             __builtin_amdgcn_fence(__ATOMIC_ACQUIRE, "agent");
;             xb_add(&bar[XB_XGEN(b.x)], 1u);
;             asm volatile("s_waitcnt vmcnt(0)" ::: "memory");
.LBB0_1005:
	s_or_b64 exec, exec, s[6:7]
	v_mov_b32_e32 v2, 0x2000
	v_mov_b32_e32 v3, 1
	s_waitcnt vmcnt(0)
	global_atomic_add v2, v3, s[4:5] offset:1024
	s_waitcnt vmcnt(0)
	s_branch .LBB0_1006

; __device__ __forceinline__ unsigned xb_ld(unsigned* p)              { return __hip_atomic_load(p, __ATOMIC_RELAXED, __HIP_MEMORY_SCOPE_AGENT); }
; #define XB_SPIN(cond, bar) do { unsigned _sp = 0; while (cond) { __builtin_amdgcn_s_sleep(1); \
;     if ((++_sp & 255u) == 0u) { if (xb_ld(&(bar)[XB_TMO])) break; if (_sp > XB_SPIN_CAP) { atomicAdd(&(bar)[XB_TMO], 1u); break; } } } } while (0)
; __device__ __forceinline__ void xcd_barrier(const XcdBarrier& b) {
;     ...
;             XB_SPIN(xb_ld(&bar[XB_XGEN(b.x)]) == gen, bar);
;             __builtin_amdgcn_fence(__ATOMIC_ACQUIRE, "agent");
;             asm volatile("s_waitcnt vmcnt(0)" ::: "memory");
.LBB0_1384:
	s_or_b64 exec, exec, s[12:13]
	s_waitcnt vmcnt(0)
	s_waitcnt vmcnt(0)

; __device__ __forceinline__ unsigned xb_add(unsigned* p, unsigned v) { return __hip_atomic_fetch_add(p, v, __ATOMIC_RELAXED, __HIP_MEMORY_SCOPE_AGENT); }
; __device__ __forceinline__ void xcd_barrier(const XcdBarrier& b) {
;     ...
;             __builtin_amdgcn_fence(__ATOMIC_ACQUIRE, "agent");
;             xb_add(&bar[XB_XGEN(b.x)], 1u);
;             asm volatile("s_waitcnt vmcnt(0)" ::: "memory");
.LBB0_1402:
	s_or_b64 exec, exec, s[10:11]
	v_mov_b32_e32 v2, 0x2000
	v_mov_b32_e32 v3, 1
	s_waitcnt vmcnt(0)
	global_atomic_add v2, v3, s[8:9] offset:1024
	s_waitcnt vmcnt(0)
	s_branch .LBB0_1403

; __device__ __forceinline__ unsigned xb_ld(unsigned* p)              { return __hip_atomic_load(p, __ATOMIC_RELAXED, __HIP_MEMORY_SCOPE_AGENT); }
; #define XB_SPIN(cond, bar) do { unsigned _sp = 0; while (cond) { __builtin_amdgcn_s_sleep(1); \
;     if ((++_sp & 255u) == 0u) { if (xb_ld(&(bar)[XB_TMO])) break; if (_sp > XB_SPIN_CAP) { atomicAdd(&(bar)[XB_TMO], 1u); break; } } } } while (0)
; __device__ __forceinline__ void xcd_barrier(const XcdBarrier& b) {
;     ...
;             XB_SPIN(xb_ld(&bar[XB_XGEN(b.x)]) == gen, bar);
;             __builtin_amdgcn_fence(__ATOMIC_ACQUIRE, "agent");
;             asm volatile("s_waitcnt vmcnt(0)" ::: "memory");
.LBB0_1475:
	s_or_b64 exec, exec, s[10:11]
	s_waitcnt vmcnt(0)
	s_waitcnt vmcnt(0)

; __device__ __forceinline__ unsigned xb_add(unsigned* p, unsigned v) { return __hip_atomic_fetch_add(p, v, __ATOMIC_RELAXED, __HIP_MEMORY_SCOPE_AGENT); }
; __device__ __forceinline__ void xcd_barrier(const XcdBarrier& b) {
;     ...
;             __builtin_amdgcn_fence(__ATOMIC_ACQUIRE, "agent");
;             xb_add(&bar[XB_XGEN(b.x)], 1u);
;             asm volatile("s_waitcnt vmcnt(0)" ::: "memory");
.LBB0_1493:
	s_or_b64 exec, exec, s[8:9]
	v_mov_b32_e32 v2, 0x2000
	v_mov_b32_e32 v3, 1
	s_waitcnt vmcnt(0)
	global_atomic_add v2, v3, s[6:7] offset:1024
	s_waitcnt vmcnt(0)
	s_branch .LBB0_1494

; __device__ __forceinline__ unsigned xb_ld(unsigned* p)              { return __hip_atomic_load(p, __ATOMIC_RELAXED, __HIP_MEMORY_SCOPE_AGENT); }
; #define XB_SPIN(cond, bar) do { unsigned _sp = 0; while (cond) { __builtin_amdgcn_s_sleep(1); \
;     if ((++_sp & 255u) == 0u) { if (xb_ld(&(bar)[XB_TMO])) break; if (_sp > XB_SPIN_CAP) { atomicAdd(&(bar)[XB_TMO], 1u); break; } } } } while (0)
; __device__ __forceinline__ void xcd_barrier(const XcdBarrier& b) {
;     ...
;             XB_SPIN(xb_ld(&bar[XB_XGEN(b.x)]) == gen, bar);
;             __builtin_amdgcn_fence(__ATOMIC_ACQUIRE, "agent");
;             asm volatile("s_waitcnt vmcnt(0)" ::: "memory");
.LBB0_1976:
	s_or_b64 exec, exec, s[6:7]
	s_waitcnt vmcnt(0)
	s_waitcnt vmcnt(0)

; __device__ __forceinline__ unsigned xb_add(unsigned* p, unsigned v) { return __hip_atomic_fetch_add(p, v, __ATOMIC_RELAXED, __HIP_MEMORY_SCOPE_AGENT); }
; __device__ __forceinline__ void xcd_barrier(const XcdBarrier& b) {
;     ...
;             __builtin_amdgcn_fence(__ATOMIC_ACQUIRE, "agent");
;             xb_add(&bar[XB_XGEN(b.x)], 1u);
;             asm volatile("s_waitcnt vmcnt(0)" ::: "memory");
.LBB0_1994:
	s_or_b64 exec, exec, s[4:5]
	v_mov_b32_e32 v2, 0x2000
	v_mov_b32_e32 v3, 1
	s_waitcnt vmcnt(0)
	global_atomic_add v2, v3, s[2:3] offset:1024
	s_waitcnt vmcnt(0)
	s_branch .LBB0_1995

; __global__ void __launch_bounds__(512, 2) mk_fwd(Args a) {
	.amdhsa_kernel _Z6mk_fwd4Args
		.amdhsa_group_segment_fixed_size 0
		.amdhsa_private_segment_fixed_size 0
		.amdhsa_kernarg_size 456
		.amdhsa_user_sgpr_count 2
		.amdhsa_user_sgpr_dispatch_ptr 0
		.amdhsa_user_sgpr_queue_ptr 0
		.amdhsa_user_sgpr_kernarg_segment_ptr 1
		.amdhsa_user_sgpr_dispatch_id 0
		.amdhsa_user_sgpr_kernarg_preload_length 0
		.amdhsa_user_sgpr_kernarg_preload_offset 0
		.amdhsa_user_sgpr_private_segment_size 0
		.amdhsa_uses_dynamic_stack 0
		.amdhsa_enable_private_segment 0
		.amdhsa_system_sgpr_workgroup_id_x 1
		.amdhsa_system_sgpr_workgroup_id_y 0
		.amdhsa_system_sgpr_workgroup_id_z 0
		.amdhsa_system_sgpr_workgroup_info 0
		.amdhsa_system_vgpr_workitem_id 2
		.amdhsa_next_free_vgpr 256
		.amdhsa_next_free_sgpr 100
		.amdhsa_accum_offset 256
		.amdhsa_reserve_vcc 1
		.amdhsa_float_round_mode_32 0
		.amdhsa_float_round_mode_16_64 0
		.amdhsa_float_denorm_mode_32 3
		.amdhsa_float_denorm_mode_16_64 3
		.amdhsa_dx10_clamp 1
		.amdhsa_ieee_mode 1
		.amdhsa_fp16_overflow 0
		.amdhsa_tg_split 0
		.amdhsa_exception_fp_ieee_invalid_op 0
		.amdhsa_exception_fp_denorm_src 0
		.amdhsa_exception_fp_ieee_div_zero 0
		.amdhsa_exception_fp_ieee_overflow 0
		.amdhsa_exception_fp_ieee_underflow 0
		.amdhsa_exception_fp_ieee_inexact 0
		.amdhsa_exception_int_div_zero 0
	.end_amdhsa_kernel

; __global__ void __launch_bounds__(512, 2) mk_fwd(Args a) {
.Lfunc_end0:
	.size	_Z6mk_fwd4Args, .Lfunc_end0-_Z6mk_fwd4Args
	.set _Z6mk_fwd4Args.num_vgpr, 256
	.set _Z6mk_fwd4Args.num_agpr, 0
	.set _Z6mk_fwd4Args.numbered_sgpr, 100
	.set _Z6mk_fwd4Args.num_named_barrier, 0
	.set _Z6mk_fwd4Args.private_seg_size, 0
	.set _Z6mk_fwd4Args.uses_vcc, 1
	.set _Z6mk_fwd4Args.uses_flat_scratch, 0
	.set _Z6mk_fwd4Args.has_dyn_sized_stack, 0
	.set _Z6mk_fwd4Args.has_recursion, 0
	.set _Z6mk_fwd4Args.has_indirect_call, 0

; __global__ void __launch_bounds__(512, 2) mk_fwd(Args a) {
amdhsa.kernels:
  - .agpr_count:     0
    .args:
      - .offset:         0
        .size:           200
        .value_kind:     by_value
      - .offset:         200
        .size:           4
        .value_kind:     hidden_block_count_x
      - .offset:         204
        .size:           4
        .value_kind:     hidden_block_count_y
      - .offset:         208
        .size:           4
        .value_kind:     hidden_block_count_z
      - .offset:         212
        .size:           2
        .value_kind:     hidden_group_size_x
      - .offset:         214
        .size:           2
        .value_kind:     hidden_group_size_y
      - .offset:         216
        .size:           2
        .value_kind:     hidden_group_size_z
      - .offset:         218
        .size:           2
        .value_kind:     hidden_remainder_x
      - .offset:         220
        .size:           2
        .value_kind:     hidden_remainder_y
      - .offset:         222
        .size:           2
        .value_kind:     hidden_remainder_z
      - .offset:         240
        .size:           8
        .value_kind:     hidden_global_offset_x
      - .offset:         248
        .size:           8
        .value_kind:     hidden_global_offset_y
      - .offset:         256
        .size:           8
        .value_kind:     hidden_global_offset_z
      - .offset:         264
        .size:           2
        .value_kind:     hidden_grid_dims
      - .offset:         288
        .size:           8
        .value_kind:     hidden_multigrid_sync_arg
      - .offset:         320
        .size:           4
        .value_kind:     hidden_dynamic_lds_size
    .group_segment_fixed_size: 0
    .kernarg_segment_align: 8
    .kernarg_segment_size: 456
    .language:       OpenCL C
    .language_version:
      - 2
      - 0
    .max_flat_workgroup_size: 512
    .name:           _Z6mk_fwd4Args
    .private_segment_fixed_size: 0
    .sgpr_count:     106
    .sgpr_spill_count: 109
    .symbol:         _Z6mk_fwd4Args.kd
    .uniform_work_group_size: 1
    .uses_dynamic_stack: false
    .vgpr_count:     256
    .vgpr_spill_count: 0
    .wavefront_size: 64
